# speedup vs baseline: 1.0313x; 1.0061x over previous
; __device__ __forceinline__ void phase_X(const Params& p, const Grp& g) {
;     ...
;         _Pragma("unroll") for (int hq = 0; hq < 4; ++hq) {
;           u32x2 zd[8]; unsigned za[8], zb[8], zc[8];
;           _Pragma("unroll") for (int q = 0; q < 8; ++q) {
;             const int f = hq * 8 + q, ai = f >> 4, bj = (f >> 3) & 1, m = (f >> 1) & 3, n = f & 1;
;             const int row = ai * 128 + t.wr * 64 + m * 16 + t.fr, col = bj * 128 + t.wc * 32 + n * 16 + t.fq * 4;
;             const int sp = pm * 256 + row, spm = (2048 - sp) & 2047, gg = col >> 6, cp = col & 63;
;             const bf16* zp = SZF + (size_t)(bl * 2048 + sp) * 512 + gg * 128 + cp;
;             const bf16* zm = SZF + (size_t)(bl * 2048 + spm) * 512 + gg * 128 + 125 - cp;
;             zd[q] = *(const u32x2*)zp;
;             za[q] = zm[0]; zb[q] = *(const unsigned*)(zm + 1); zc[q] = (cp != 0) ? zm[3] : 0u;
;           }
.LBB0_598:
	v_lshrrev_b32_e32 v130, 6, v130
	v_lshlrev_b32_e32 v130, 5, v130
	s_lshl_b32 s14, s4, 11
	v_lshlrev_b32_e32 v129, 6, v129
	v_lshl_add_u32 v172, v128, 6, v132
	v_and_or_b32 v136, v130, 32, v131
	v_and_b32_e32 v173, 0x80, v129
	v_add_u32_e32 v130, s14, v172
	v_lshlrev_b32_e32 v132, 1, v173
	v_mov_b32_e32 v133, v187
	v_ashrrev_i32_e32 v131, 31, v130
	v_lshl_add_u64 v[134:135], s[8:9], 0, v[132:133]
	v_sub_u32_e32 v128, 0, v172
	v_lshlrev_b64 v[148:149], 10, v[130:131]
	v_and_b32_e32 v133, 0x7ff, v128
	v_lshl_add_u64 v[128:129], v[134:135], 0, v[148:149]
	v_lshlrev_b32_e32 v186, 1, v136
	v_lshl_add_u64 v[138:139], v[128:129], 0, v[186:187]
	v_or_b32_e32 v128, s14, v133
	v_ashrrev_i32_e32 v129, 31, v128
	v_lshlrev_b64 v[150:151], 10, v[128:129]
	v_lshl_add_u64 v[128:129], v[134:135], 0, v[150:151]
	v_sub_co_u32_e32 v140, vcc, v128, v186
	v_mov_b32_e32 v198, 0
	s_nop 0
	v_subbrev_co_u32_e32 v141, vcc, 0, v129, vcc
	global_load_dwordx2 v[166:167], v[138:139], off
	global_load_ushort v212, v[140:141], off offset:250
	global_load_dword v211, v[140:141], off offset:252
	v_cmp_ne_u32_e32 vcc, 0, v136
	v_mov_b32_e32 v210, 0
	s_and_saveexec_b64 s[0:1], vcc
	s_cbranch_execz .LBB0_600
	global_load_ushort v210, v[140:141], off offset:256
.LBB0_600:
	s_or_b64 exec, exec, s[0:1]
	v_or_b32_e32 v131, 16, v172
	global_load_dwordx2 v[164:165], v[138:139], off offset:32
	global_load_ushort v209, v[140:141], off offset:218
	global_load_dword v208, v[140:141], off offset:220
	global_load_ushort v207, v[140:141], off offset:224
	v_add_u32_e32 v138, s14, v131
	v_ashrrev_i32_e32 v139, 31, v138
	v_sub_u32_e32 v133, 0, v131
	v_lshlrev_b64 v[144:145], 10, v[138:139]
	v_and_b32_e32 v133, 0x7ff, v133
	v_lshl_add_u64 v[138:139], v[134:135], 0, v[144:145]
	v_lshlrev_b32_e32 v186, 1, v136
	v_sub_co_u32_e64 v128, s[4:5], 0, v136
	v_lshl_add_u64 v[136:137], v[138:139], 0, v[186:187]
	v_or_b32_e32 v138, s14, v133
	v_ashrrev_i32_e32 v139, 31, v138
	v_lshlrev_b64 v[146:147], 10, v[138:139]
	v_subb_co_u32_e64 v129, s[0:1], 0, 0, s[4:5]
	v_lshl_add_u64 v[138:139], v[134:135], 0, v[146:147]
	v_lshl_add_u64 v[138:139], v[128:129], 1, v[138:139]
	global_load_dwordx2 v[162:163], v[136:137], off
	global_load_ushort v206, v[138:139], off offset:250
	global_load_dword v205, v[138:139], off offset:252
	s_and_saveexec_b64 s[0:1], vcc
	s_cbranch_execz .LBB0_602
	global_load_ushort v198, v[138:139], off offset:256
.LBB0_602:
	s_or_b64 exec, exec, s[0:1]
	v_or_b32_e32 v131, 32, v172
	v_sub_u32_e32 v133, 0, v131
	global_load_dwordx2 v[160:161], v[136:137], off offset:32
	global_load_ushort v204, v[138:139], off offset:218
	global_load_dword v203, v[138:139], off offset:220
	global_load_ushort v202, v[138:139], off offset:224
	v_and_b32_e32 v133, 0x7ff, v133
	v_add_u32_e32 v136, s14, v131
	v_ashrrev_i32_e32 v137, 31, v136
	v_or_b32_e32 v138, s14, v133
	v_lshlrev_b64 v[140:141], 10, v[136:137]
	v_ashrrev_i32_e32 v139, 31, v138
	v_lshl_add_u64 v[136:137], v[134:135], 0, v[140:141]
	v_lshlrev_b64 v[142:143], 10, v[138:139]
	v_lshl_add_u64 v[136:137], v[136:137], 0, v[186:187]
	v_lshl_add_u64 v[138:139], v[134:135], 0, v[142:143]
	v_lshl_add_u64 v[138:139], v[128:129], 1, v[138:139]
	global_load_dwordx2 v[158:159], v[136:137], off
	global_load_ushort v201, v[138:139], off offset:250
	global_load_dword v200, v[138:139], off offset:252
	v_mov_b32_e32 v131, 0
	v_mov_b32_e32 v199, 0
	s_and_saveexec_b64 s[0:1], vcc
	s_cbranch_execz .LBB0_604
	global_load_ushort v199, v[138:139], off offset:256

; __device__ __forceinline__ bf16 f2bf(float f) { return (bf16)(pack2(f, 0.f) & 0xffffu); }
; __device__ __forceinline__ float bf2f(bf16 h) { return __uint_as_float(((unsigned)h) << 16); }
; #define SCHED __builtin_amdgcn_sched_barrier(0)
; __device__ __forceinline__ void phase_X(const Params& p, const Grp& g) {
;     ...
;             za[q] = zm[0]; zb[q] = *(const unsigned*)(zm + 1); zc[q] = (cp != 0) ? zm[3] : 0u;
;           }
;           SCHED;
;           _Pragma("unroll") for (int q = 0; q < 8; ++q) {
;             const int f = hq * 8 + q, ai = f >> 4, bj = (f >> 3) & 1, m = (f >> 1) & 3, n = f & 1;
;             const int row = ai * 128 + t.wr * 64 + m * 16 + t.fr, col = bj * 128 + t.wc * 32 + n * 16 + t.fq * 4;
;             const int sp = pm * 256 + row, spm = (2048 - sp) & 2047, gg = col >> 6, cp = col & 63;
;             bf16* yp = YF + (size_t)(bl * 2048 + sp) * 512 + gg * 128 + cp;
;             bf16* ym = YF + (size_t)(bl * 2048 + spm) * 512 + gg * 128 + 125 - cp;
;             f32x4 vv = acc[ai][bj][m][n];
;             float z0, z1, z2, z3; unpack4(make_uint2(zd[q][0], zd[q][1]), z0, z1, z2, z3);
;             *(uint2*)yp = pack4(vv[0] * z0, vv[1] * z1, vv[2] * z2, vv[3] * z3);
;             const float ma = bf2f((bf16)za[q]), mb0 = __uint_as_float(zb[q] << 16), mb1 = __uint_as_float(zb[q] & 0xffff0000u), mc = bf2f((bf16)zc[q]);
;             ym[0] = f2bf(vv[3] * ma);
;             *(unsigned*)(ym + 1) = pack2(vv[2] * mb0, vv[1] * mb1);
;             if (cp != 0) ym[3] = f2bf(vv[0] * mc);
.LBB0_606:
	s_or_b64 exec, exec, s[0:1]
	global_load_dwordx2 v[152:153], v[152:153], off offset:32
	s_nop 0
	global_load_ushort v176, v[168:169], off offset:218
	global_load_dword v175, v[168:169], off offset:220
	global_load_ushort v174, v[168:169], off offset:224
	v_mov_b32_e32 v133, v187
	s_waitcnt vmcnt(0)
	v_lshlrev_b32_e32 v210, 16, v210
	v_lshlrev_b32_e32 v198, 16, v198
	v_lshlrev_b32_e32 v199, 16, v199
	v_lshlrev_b32_e32 v131, 16, v131
	v_lshlrev_b32_e32 v214, 16, v166
	v_and_b32_e32 v215, 0xffff0000, v166
	v_lshlrev_b32_e32 v166, 16, v167
	v_and_b32_e32 v167, 0xffff0000, v167
	v_lshlrev_b32_e32 v212, 16, v212
	v_lshl_add_u64 v[132:133], s[10:11], 0, v[132:133]
	v_pk_mul_f32 v[214:215], v[124:125], v[214:215]
	v_pk_mul_f32 v[166:167], v[126:127], v[166:167]
	v_mul_f32_e32 v127, v127, v212
	v_lshl_add_u64 v[168:169], v[132:133], 0, v[148:149]
	v_cvt_pk_bf16_f32 v214, v214, v215
	v_cvt_pk_bf16_f32 v215, v166, v167
	v_lshlrev_b32_e32 v166, 16, v211
	v_and_b32_e32 v167, 0xffff0000, v211
	v_cvt_pk_bf16_f32 v211, v127, s0
	v_mov_b32_e32 v127, v125
	v_lshl_add_u64 v[170:171], v[168:169], 0, v[186:187]
	v_lshl_add_u64 v[168:169], v[132:133], 0, v[150:151]
	v_pk_mul_f32 v[126:127], v[126:127], v[166:167]
	v_lshl_add_u64 v[168:169], v[128:129], 1, v[168:169]
	v_cvt_pk_bf16_f32 v125, v126, v127
	s_mov_b32 s0, 0x5040100
	global_store_dwordx2 v[170:171], v[214:215], off
	v_perm_b32 v126, v125, v211, s0
	global_store_short_d16_hi v[168:169], v125, off offset:254
	global_store_dword v[168:169], v126, off offset:250
	s_and_saveexec_b64 s[0:1], vcc
	s_cbranch_execz .LBB0_608
	v_mul_f32_e32 v124, v124, v210
	v_cvt_pk_bf16_f32 v124, v124, s0
	global_store_short v[168:169], v124, off offset:256

; __device__ __forceinline__ bf16 f2bf(float f) { return (bf16)(pack2(f, 0.f) & 0xffffu); }
; __device__ __forceinline__ float bf2f(bf16 h) { return __uint_as_float(((unsigned)h) << 16); }
; #define SCHED __builtin_amdgcn_sched_barrier(0)
; __device__ __forceinline__ void phase_X(const Params& p, const Grp& g) {
;     ...
;         _Pragma("unroll") for (int hq = 0; hq < 4; ++hq) {
;           u32x2 zd[8]; unsigned za[8], zb[8], zc[8];
;           _Pragma("unroll") for (int q = 0; q < 8; ++q) {
;             const int f = hq * 8 + q, ai = f >> 4, bj = (f >> 3) & 1, m = (f >> 1) & 3, n = f & 1;
;             const int row = ai * 128 + t.wr * 64 + m * 16 + t.fr, col = bj * 128 + t.wc * 32 + n * 16 + t.fq * 4;
;             const int sp = pm * 256 + row, spm = (2048 - sp) & 2047, gg = col >> 6, cp = col & 63;
;             const bf16* zp = SZF + (size_t)(bl * 2048 + sp) * 512 + gg * 128 + cp;
;             const bf16* zm = SZF + (size_t)(bl * 2048 + spm) * 512 + gg * 128 + 125 - cp;
;             zd[q] = *(const u32x2*)zp;
;             za[q] = zm[0]; zb[q] = *(const unsigned*)(zm + 1); zc[q] = (cp != 0) ? zm[3] : 0u;
;           }
;           SCHED;
;           _Pragma("unroll") for (int q = 0; q < 8; ++q) {
;             const int f = hq * 8 + q, ai = f >> 4, bj = (f >> 3) & 1, m = (f >> 1) & 3, n = f & 1;
;             const int row = ai * 128 + t.wr * 64 + m * 16 + t.fr, col = bj * 128 + t.wc * 32 + n * 16 + t.fq * 4;
;             const int sp = pm * 256 + row, spm = (2048 - sp) & 2047, gg = col >> 6, cp = col & 63;
;             bf16* yp = YF + (size_t)(bl * 2048 + sp) * 512 + gg * 128 + cp;
;             bf16* ym = YF + (size_t)(bl * 2048 + spm) * 512 + gg * 128 + 125 - cp;
;             f32x4 vv = acc[ai][bj][m][n];
;             float z0, z1, z2, z3; unpack4(make_uint2(zd[q][0], zd[q][1]), z0, z1, z2, z3);
;             *(uint2*)yp = pack4(vv[0] * z0, vv[1] * z1, vv[2] * z2, vv[3] * z3);
;             const float ma = bf2f((bf16)za[q]), mb0 = __uint_as_float(zb[q] << 16), mb1 = __uint_as_float(zb[q] & 0xffff0000u), mc = bf2f((bf16)zc[q]);
;             ym[0] = f2bf(vv[3] * ma);
;             *(unsigned*)(ym + 1) = pack2(vv[2] * mb0, vv[1] * mb1);
;             if (cp != 0) ym[3] = f2bf(vv[0] * mc);
.LBB0_614:
	s_or_b64 exec, exec, s[0:1]
	v_lshlrev_b32_e32 v100, 16, v152
	v_and_b32_e32 v101, 0xffff0000, v152
	v_lshlrev_b32_e32 v102, 16, v153
	v_and_b32_e32 v103, 0xffff0000, v153
	v_pk_mul_f32 v[100:101], v[96:97], v[100:101]
	v_pk_mul_f32 v[102:103], v[98:99], v[102:103]
	v_cvt_pk_bf16_f32 v100, v100, v101
	v_cvt_pk_bf16_f32 v101, v102, v103
	v_lshlrev_b32_e32 v102, 16, v176
	v_mul_f32_e32 v99, v99, v102
	global_store_dwordx2 v[106:107], v[100:101], off offset:32
	v_lshlrev_b32_e32 v100, 16, v175
	v_and_b32_e32 v101, 0xffff0000, v175
	v_cvt_pk_bf16_f32 v102, v99, s0
	v_mov_b32_e32 v99, v97
	v_pk_mul_f32 v[98:99], v[98:99], v[100:101]
	s_nop 0
	v_cvt_pk_bf16_f32 v97, v98, v99
	v_lshlrev_b32_e32 v98, 16, v174
	v_mul_f32_e32 v96, v96, v98
	v_cvt_pk_bf16_f32 v98, v96, s0
	v_perm_b32 v96, v97, v102, s15
	v_alignbit_b32 v97, v98, v97, 16
	global_store_dwordx2 v[104:105], v[96:97], off offset:218
	v_or_b32_e32 v96, 0x100, v173
	v_lshl_add_u64 v[98:99], s[8:9], 0, v[148:149]
	v_lshl_add_u64 v[100:101], v[98:99], 0, v[186:187]
	v_lshlrev_b32_e32 v96, 1, v96
	v_mov_b32_e32 v97, v187
	v_lshl_add_u64 v[102:103], v[100:101], 0, v[96:97]
	v_lshl_add_u64 v[100:101], s[8:9], 0, v[150:151]
	v_lshl_add_u64 v[100:101], v[100:101], 0, v[96:97]
	v_lshl_add_u64 v[100:101], v[128:129], 1, v[100:101]
	global_load_dwordx2 v[112:113], v[102:103], off
	global_load_ushort v164, v[100:101], off offset:250
	global_load_dword v163, v[100:101], off offset:252
	v_mov_b32_e32 v123, 0
	v_mov_b32_e32 v162, 0
	s_and_saveexec_b64 s[0:1], vcc
	s_cbranch_execz .LBB0_616
	global_load_ushort v162, v[100:101], off offset:256
.LBB0_616:
	s_or_b64 exec, exec, s[0:1]
	v_lshl_add_u64 v[98:99], v[98:99], 0, v[96:97]
	v_lshl_add_u64 v[98:99], v[98:99], 0, v[186:187]
	global_load_dwordx2 v[110:111], v[98:99], off offset:32
	global_load_ushort v161, v[100:101], off offset:218
	global_load_dword v160, v[100:101], off offset:220
	global_load_ushort v158, v[100:101], off offset:224
	v_lshl_add_u64 v[98:99], s[8:9], 0, v[144:145]
	v_lshl_add_u64 v[100:101], v[98:99], 0, v[186:187]
	v_lshl_add_u64 v[102:103], v[100:101], 0, v[96:97]
	v_lshl_add_u64 v[100:101], s[8:9], 0, v[146:147]
	v_lshl_add_u64 v[100:101], v[100:101], 0, v[96:97]
	v_lshl_add_u64 v[100:101], v[128:129], 1, v[100:101]
	global_load_dwordx2 v[108:109], v[102:103], off
	global_load_ushort v159, v[100:101], off offset:250
	global_load_dword v157, v[100:101], off offset:252
	s_and_saveexec_b64 s[0:1], vcc
	s_cbranch_execz .LBB0_618
	global_load_ushort v123, v[100:101], off offset:256
.LBB0_618:
	s_or_b64 exec, exec, s[0:1]
	v_mov_b32_e32 v97, v187
	v_lshl_add_u64 v[98:99], v[98:99], 0, v[96:97]
	v_lshl_add_u64 v[98:99], v[98:99], 0, v[186:187]
	global_load_dwordx2 v[106:107], v[98:99], off offset:32
	global_load_ushort v156, v[100:101], off offset:218
	global_load_dword v155, v[100:101], off offset:220
	global_load_ushort v153, v[100:101], off offset:224
	v_lshl_add_u64 v[100:101], s[8:9], 0, v[140:141]
	v_lshl_add_u64 v[98:99], v[100:101], 0, v[186:187]
	v_lshl_add_u64 v[102:103], v[98:99], 0, v[96:97]
	v_lshl_add_u64 v[98:99], s[8:9], 0, v[142:143]
	v_lshl_add_u64 v[98:99], v[98:99], 0, v[96:97]
	v_lshl_add_u64 v[98:99], v[128:129], 1, v[98:99]
	global_load_dwordx2 v[104:105], v[102:103], off
	global_load_ushort v154, v[98:99], off offset:250
	global_load_dword v152, v[98:99], off offset:252
	v_mov_b32_e32 v118, 0
	v_mov_b32_e32 v131, 0
	s_and_saveexec_b64 s[0:1], vcc
	s_cbranch_execz .LBB0_620
	global_load_ushort v131, v[98:99], off offset:256
.LBB0_620:
	s_or_b64 exec, exec, s[0:1]
	v_lshl_add_u64 v[100:101], v[100:101], 0, v[96:97]
	v_lshl_add_u64 v[100:101], v[100:101], 0, v[186:187]
	global_load_dwordx2 v[102:103], v[100:101], off offset:32
	global_load_ushort v127, v[98:99], off offset:218
	global_load_dword v126, v[98:99], off offset:220
	global_load_ushort v124, v[98:99], off offset:224
	v_lshl_add_u64 v[98:99], s[8:9], 0, v[136:137]
	v_lshl_add_u64 v[100:101], v[98:99], 0, v[186:187]
	v_lshl_add_u64 v[114:115], s[8:9], 0, v[138:139]
	v_lshl_add_u64 v[100:101], v[100:101], 0, v[96:97]
	v_lshl_add_u64 v[114:115], v[114:115], 0, v[96:97]
	v_lshl_add_u64 v[114:115], v[128:129], 1, v[114:115]
	global_load_dwordx2 v[100:101], v[100:101], off
	s_nop 0
	global_load_ushort v125, v[114:115], off offset:250
	global_load_dword v122, v[114:115], off offset:252
	s_and_saveexec_b64 s[0:1], vcc
	s_cbranch_execz .LBB0_622
	global_load_ushort v118, v[114:115], off offset:256
.LBB0_622:
	s_or_b64 exec, exec, s[0:1]
	v_mov_b32_e32 v97, v187
	v_lshl_add_u64 v[98:99], v[98:99], 0, v[96:97]
	v_lshl_add_u64 v[98:99], v[98:99], 0, v[186:187]
	global_load_dwordx2 v[98:99], v[98:99], off offset:32
	s_nop 0
	global_load_ushort v121, v[114:115], off offset:218
	global_load_dword v120, v[114:115], off offset:220
	global_load_ushort v119, v[114:115], off offset:224
	v_lshl_add_u64 v[116:117], s[10:11], 0, v[148:149]
	v_lshl_add_u64 v[114:115], v[116:117], 0, v[186:187]
	v_lshl_add_u64 v[148:149], v[114:115], 0, v[96:97]
	v_lshl_add_u64 v[114:115], s[10:11], 0, v[150:151]
	s_waitcnt vmcnt(0)
	v_lshlrev_b32_e32 v162, 16, v162
	v_lshlrev_b32_e32 v123, 16, v123
	v_lshlrev_b32_e32 v131, 16, v131
	v_lshlrev_b32_e32 v118, 16, v118
	v_lshlrev_b32_e32 v150, 16, v112
	v_and_b32_e32 v151, 0xffff0000, v112
	v_lshlrev_b32_e32 v112, 16, v113
	v_and_b32_e32 v113, 0xffff0000, v113
	v_pk_mul_f32 v[150:151], v[92:93], v[150:151]
	v_pk_mul_f32 v[112:113], v[94:95], v[112:113]
	v_cvt_pk_bf16_f32 v150, v150, v151
	v_cvt_pk_bf16_f32 v151, v112, v113
	global_store_dwordx2 v[148:149], v[150:151], off
	v_lshlrev_b32_e32 v148, 16, v164
	v_mul_f32_e32 v95, v95, v148
	v_lshlrev_b32_e32 v112, 16, v163
	v_and_b32_e32 v113, 0xffff0000, v163
	v_cvt_pk_bf16_f32 v148, v95, s0
	v_mov_b32_e32 v95, v93
	v_lshl_add_u64 v[114:115], v[114:115], 0, v[96:97]
	v_pk_mul_f32 v[94:95], v[94:95], v[112:113]
	v_lshl_add_u64 v[114:115], v[128:129], 1, v[114:115]
	v_cvt_pk_bf16_f32 v93, v94, v95
	v_perm_b32 v94, v93, v148, s15
	global_store_short_d16_hi v[114:115], v93, off offset:254
	global_store_dword v[114:115], v94, off offset:250
	s_and_saveexec_b64 s[0:1], vcc
	s_cbranch_execz .LBB0_624
	v_mul_f32_e32 v92, v92, v162
	v_cvt_pk_bf16_f32 v92, v92, s0
	global_store_short v[114:115], v92, off offset:256

; __device__ __forceinline__ bf16 f2bf(float f) { return (bf16)(pack2(f, 0.f) & 0xffffu); }
; __device__ __forceinline__ float bf2f(bf16 h) { return __uint_as_float(((unsigned)h) << 16); }
; #define SCHED __builtin_amdgcn_sched_barrier(0)
; __device__ __forceinline__ void phase_X(const Params& p, const Grp& g) {
;     ...
;         _Pragma("unroll") for (int hq = 0; hq < 4; ++hq) {
;           u32x2 zd[8]; unsigned za[8], zb[8], zc[8];
;           _Pragma("unroll") for (int q = 0; q < 8; ++q) {
;             const int f = hq * 8 + q, ai = f >> 4, bj = (f >> 3) & 1, m = (f >> 1) & 3, n = f & 1;
;             const int row = ai * 128 + t.wr * 64 + m * 16 + t.fr, col = bj * 128 + t.wc * 32 + n * 16 + t.fq * 4;
;             const int sp = pm * 256 + row, spm = (2048 - sp) & 2047, gg = col >> 6, cp = col & 63;
;             const bf16* zp = SZF + (size_t)(bl * 2048 + sp) * 512 + gg * 128 + cp;
;             const bf16* zm = SZF + (size_t)(bl * 2048 + spm) * 512 + gg * 128 + 125 - cp;
;             zd[q] = *(const u32x2*)zp;
;             za[q] = zm[0]; zb[q] = *(const unsigned*)(zm + 1); zc[q] = (cp != 0) ? zm[3] : 0u;
;           }
;           SCHED;
;           _Pragma("unroll") for (int q = 0; q < 8; ++q) {
;             const int f = hq * 8 + q, ai = f >> 4, bj = (f >> 3) & 1, m = (f >> 1) & 3, n = f & 1;
;             const int row = ai * 128 + t.wr * 64 + m * 16 + t.fr, col = bj * 128 + t.wc * 32 + n * 16 + t.fq * 4;
;             const int sp = pm * 256 + row, spm = (2048 - sp) & 2047, gg = col >> 6, cp = col & 63;
;             bf16* yp = YF + (size_t)(bl * 2048 + sp) * 512 + gg * 128 + cp;
;             bf16* ym = YF + (size_t)(bl * 2048 + spm) * 512 + gg * 128 + 125 - cp;
;             f32x4 vv = acc[ai][bj][m][n];
;             float z0, z1, z2, z3; unpack4(make_uint2(zd[q][0], zd[q][1]), z0, z1, z2, z3);
;             *(uint2*)yp = pack4(vv[0] * z0, vv[1] * z1, vv[2] * z2, vv[3] * z3);
;             const float ma = bf2f((bf16)za[q]), mb0 = __uint_as_float(zb[q] << 16), mb1 = __uint_as_float(zb[q] & 0xffff0000u), mc = bf2f((bf16)zc[q]);
;             ym[0] = f2bf(vv[3] * ma);
;             *(unsigned*)(ym + 1) = pack2(vv[2] * mb0, vv[1] * mb1);
;             if (cp != 0) ym[3] = f2bf(vv[0] * mc);
.LBB0_630:
	s_or_b64 exec, exec, s[0:1]
	v_mov_b32_e32 v97, v187
	v_lshl_add_u64 v[68:69], v[74:75], 0, v[96:97]
	v_lshlrev_b32_e32 v70, 16, v98
	v_and_b32_e32 v71, 0xffff0000, v98
	v_lshlrev_b32_e32 v74, 16, v99
	v_and_b32_e32 v75, 0xffff0000, v99
	v_pk_mul_f32 v[70:71], v[64:65], v[70:71]
	v_pk_mul_f32 v[74:75], v[66:67], v[74:75]
	v_lshl_add_u64 v[68:69], v[68:69], 0, v[186:187]
	v_cvt_pk_bf16_f32 v70, v70, v71
	v_cvt_pk_bf16_f32 v71, v74, v75
	global_store_dwordx2 v[68:69], v[70:71], off offset:32
	v_lshlrev_b32_e32 v70, 16, v121
	v_mul_f32_e32 v67, v67, v70
	v_lshlrev_b32_e32 v68, 16, v120
	v_and_b32_e32 v69, 0xffff0000, v120
	v_cvt_pk_bf16_f32 v70, v67, s0
	v_mov_b32_e32 v67, v65
	v_pk_mul_f32 v[66:67], v[66:67], v[68:69]
	s_nop 0
	v_cvt_pk_bf16_f32 v65, v66, v67
	v_lshlrev_b32_e32 v66, 16, v119
	v_mul_f32_e32 v64, v64, v66
	v_cvt_pk_bf16_f32 v66, v64, s0
	v_perm_b32 v64, v65, v70, s15
	v_alignbit_b32 v65, v66, v65, 16
	global_store_dwordx2 v[72:73], v[64:65], off offset:218
	v_add_u32_e32 v68, 0x80, v172
	v_sub_u32_e32 v64, 0xffffff80, v172
	v_and_b32_e32 v66, 0x7ff, v64
	v_add_u32_e32 v64, s14, v68
	v_ashrrev_i32_e32 v65, 31, v64
	v_or_b32_e32 v66, s14, v66
	v_lshlrev_b64 v[80:81], 10, v[64:65]
	v_ashrrev_i32_e32 v67, 31, v66
	v_lshl_add_u64 v[64:65], v[134:135], 0, v[80:81]
	v_lshlrev_b64 v[82:83], 10, v[66:67]
	v_lshl_add_u64 v[64:65], v[64:65], 0, v[186:187]
	v_lshl_add_u64 v[66:67], v[134:135], 0, v[82:83]
	v_lshl_add_u64 v[66:67], v[128:129], 1, v[66:67]
	global_load_dwordx2 v[100:101], v[64:65], off
	global_load_ushort v131, v[66:67], off offset:250
	global_load_dword v127, v[66:67], off offset:252
	v_mov_b32_e32 v117, 0
	v_mov_b32_e32 v126, 0
	s_and_saveexec_b64 s[0:1], vcc
	s_cbranch_execz .LBB0_632
	global_load_ushort v126, v[66:67], off offset:256
.LBB0_632:
	s_or_b64 exec, exec, s[0:1]
	global_load_dwordx2 v[98:99], v[64:65], off offset:32
	global_load_ushort v125, v[66:67], off offset:218
	global_load_dword v124, v[66:67], off offset:220
	global_load_ushort v123, v[66:67], off offset:224
	v_or_b32_e32 v64, 16, v68
	v_sub_u32_e32 v65, 0, v64
	v_and_b32_e32 v66, 0x7ff, v65
	v_add_u32_e32 v64, s14, v64
	v_ashrrev_i32_e32 v65, 31, v64
	v_or_b32_e32 v66, s14, v66
	v_lshlrev_b64 v[76:77], 10, v[64:65]
	v_ashrrev_i32_e32 v67, 31, v66
	v_lshl_add_u64 v[64:65], v[134:135], 0, v[76:77]
	v_lshlrev_b64 v[78:79], 10, v[66:67]
	v_lshl_add_u64 v[64:65], v[64:65], 0, v[186:187]
	v_lshl_add_u64 v[66:67], v[134:135], 0, v[78:79]
	v_lshl_add_u64 v[66:67], v[128:129], 1, v[66:67]
	global_load_dwordx2 v[94:95], v[64:65], off
	global_load_ushort v122, v[66:67], off offset:250
	global_load_dword v121, v[66:67], off offset:252
	s_and_saveexec_b64 s[0:1], vcc
	s_cbranch_execz .LBB0_634
	global_load_ushort v117, v[66:67], off offset:256
.LBB0_634:
	s_or_b64 exec, exec, s[0:1]
	global_load_dwordx2 v[92:93], v[64:65], off offset:32
	global_load_ushort v120, v[66:67], off offset:218
	global_load_dword v119, v[66:67], off offset:220
	global_load_ushort v118, v[66:67], off offset:224
	v_or_b32_e32 v64, 32, v68
	v_sub_u32_e32 v65, 0, v64
	v_and_b32_e32 v66, 0x7ff, v65
	v_add_u32_e32 v64, s14, v64
	v_ashrrev_i32_e32 v65, 31, v64
	v_or_b32_e32 v66, s14, v66
	v_lshlrev_b64 v[72:73], 10, v[64:65]
	v_ashrrev_i32_e32 v67, 31, v66
	v_lshl_add_u64 v[64:65], v[134:135], 0, v[72:73]
	v_lshlrev_b64 v[74:75], 10, v[66:67]
	v_lshl_add_u64 v[64:65], v[64:65], 0, v[186:187]
	v_lshl_add_u64 v[66:67], v[134:135], 0, v[74:75]
	v_lshl_add_u64 v[66:67], v[128:129], 1, v[66:67]
	global_load_dwordx2 v[90:91], v[64:65], off
	global_load_ushort v116, v[66:67], off offset:250
	global_load_dword v115, v[66:67], off offset:252
	v_mov_b32_e32 v97, 0
	v_mov_b32_e32 v114, 0
	s_and_saveexec_b64 s[0:1], vcc
	s_cbranch_execz .LBB0_636
	global_load_ushort v114, v[66:67], off offset:256
.LBB0_636:
	s_or_b64 exec, exec, s[0:1]
	global_load_dwordx2 v[88:89], v[64:65], off offset:32
	global_load_ushort v113, v[66:67], off offset:218
	global_load_dword v112, v[66:67], off offset:220
	global_load_ushort v111, v[66:67], off offset:224
	v_or_b32_e32 v64, 48, v68
	v_sub_u32_e32 v65, 0, v64
	v_and_b32_e32 v68, 0x7df, v65
	v_add_u32_e32 v64, s14, v64
	v_ashrrev_i32_e32 v65, 31, v64
	v_or_b32_e32 v68, s14, v68
	v_lshlrev_b64 v[66:67], 10, v[64:65]
	v_ashrrev_i32_e32 v69, 31, v68
	v_lshl_add_u64 v[64:65], v[134:135], 0, v[66:67]
	v_lshlrev_b64 v[70:71], 10, v[68:69]
	v_lshl_add_u64 v[64:65], v[64:65], 0, v[186:187]
	v_lshl_add_u64 v[68:69], v[134:135], 0, v[70:71]
	v_lshl_add_u64 v[68:69], v[128:129], 1, v[68:69]
	global_load_dwordx2 v[86:87], v[64:65], off
	global_load_ushort v110, v[68:69], off offset:250
	global_load_dword v109, v[68:69], off offset:252
	s_and_saveexec_b64 s[0:1], vcc
	s_cbranch_execz .LBB0_638
	global_load_ushort v97, v[68:69], off offset:256
.LBB0_638:
	s_or_b64 exec, exec, s[0:1]
	global_load_dwordx2 v[84:85], v[64:65], off offset:32
	global_load_ushort v108, v[68:69], off offset:218
	global_load_dword v107, v[68:69], off offset:220
	global_load_ushort v106, v[68:69], off offset:224
	v_sub_u32_e32 v64, 0x780, v172
	v_and_b32_e32 v102, 0x7ff, v64
	v_add_u32_e32 v64, 0x80, v130
	v_ashrrev_i32_e32 v65, 31, v64
	v_lshlrev_b64 v[64:65], 10, v[64:65]
	v_lshl_add_u64 v[68:69], v[132:133], 0, v[64:65]
	v_lshl_add_u64 v[104:105], v[68:69], 0, v[186:187]
	v_or_b32_e32 v68, s14, v102
	s_waitcnt vmcnt(0)
	v_lshlrev_b32_e32 v126, 16, v126
	v_lshlrev_b32_e32 v117, 16, v117
	v_lshlrev_b32_e32 v114, 16, v114
	v_lshlrev_b32_e32 v97, 16, v97
	v_lshlrev_b32_e32 v134, 16, v100
	v_and_b32_e32 v135, 0xffff0000, v100
	v_lshlrev_b32_e32 v100, 16, v101
	v_and_b32_e32 v101, 0xffff0000, v101
	v_lshlrev_b32_e32 v131, 16, v131
	v_ashrrev_i32_e32 v69, 31, v68
	v_pk_mul_f32 v[134:135], v[60:61], v[134:135]
	v_pk_mul_f32 v[100:101], v[62:63], v[100:101]
	v_mul_f32_e32 v63, v63, v131
	v_lshlrev_b64 v[68:69], 10, v[68:69]
	v_cvt_pk_bf16_f32 v134, v134, v135
	v_cvt_pk_bf16_f32 v135, v100, v101
	v_lshlrev_b32_e32 v100, 16, v127
	v_and_b32_e32 v101, 0xffff0000, v127
	v_cvt_pk_bf16_f32 v127, v63, s0
	v_mov_b32_e32 v63, v61
	v_lshl_add_u64 v[102:103], v[132:133], 0, v[68:69]
	v_pk_mul_f32 v[62:63], v[62:63], v[100:101]
	v_lshl_add_u64 v[102:103], v[128:129], 1, v[102:103]
	v_cvt_pk_bf16_f32 v61, v62, v63
	global_store_dwordx2 v[104:105], v[134:135], off
	v_perm_b32 v62, v61, v127, s15
	global_store_short_d16_hi v[102:103], v61, off offset:254
	global_store_dword v[102:103], v62, off offset:250
	s_and_saveexec_b64 s[0:1], vcc
	s_cbranch_execz .LBB0_640
	v_mul_f32_e32 v60, v60, v126
	v_cvt_pk_bf16_f32 v60, v60, s0
	global_store_short v[102:103], v60, off offset:256

; __device__ __forceinline__ bf16 f2bf(float f) { return (bf16)(pack2(f, 0.f) & 0xffffu); }
; __device__ __forceinline__ float bf2f(bf16 h) { return __uint_as_float(((unsigned)h) << 16); }
; #define SCHED __builtin_amdgcn_sched_barrier(0)
; __device__ __forceinline__ void phase_X(const Params& p, const Grp& g) {
;     ...
;         _Pragma("unroll") for (int hq = 0; hq < 4; ++hq) {
;           u32x2 zd[8]; unsigned za[8], zb[8], zc[8];
;           _Pragma("unroll") for (int q = 0; q < 8; ++q) {
;             const int f = hq * 8 + q, ai = f >> 4, bj = (f >> 3) & 1, m = (f >> 1) & 3, n = f & 1;
;             const int row = ai * 128 + t.wr * 64 + m * 16 + t.fr, col = bj * 128 + t.wc * 32 + n * 16 + t.fq * 4;
;             const int sp = pm * 256 + row, spm = (2048 - sp) & 2047, gg = col >> 6, cp = col & 63;
;             const bf16* zp = SZF + (size_t)(bl * 2048 + sp) * 512 + gg * 128 + cp;
;             const bf16* zm = SZF + (size_t)(bl * 2048 + spm) * 512 + gg * 128 + 125 - cp;
;             zd[q] = *(const u32x2*)zp;
;             za[q] = zm[0]; zb[q] = *(const unsigned*)(zm + 1); zc[q] = (cp != 0) ? zm[3] : 0u;
;           }
;           SCHED;
;           _Pragma("unroll") for (int q = 0; q < 8; ++q) {
;             const int f = hq * 8 + q, ai = f >> 4, bj = (f >> 3) & 1, m = (f >> 1) & 3, n = f & 1;
;             const int row = ai * 128 + t.wr * 64 + m * 16 + t.fr, col = bj * 128 + t.wc * 32 + n * 16 + t.fq * 4;
;             const int sp = pm * 256 + row, spm = (2048 - sp) & 2047, gg = col >> 6, cp = col & 63;
;             bf16* yp = YF + (size_t)(bl * 2048 + sp) * 512 + gg * 128 + cp;
;             bf16* ym = YF + (size_t)(bl * 2048 + spm) * 512 + gg * 128 + 125 - cp;
;             f32x4 vv = acc[ai][bj][m][n];
;             float z0, z1, z2, z3; unpack4(make_uint2(zd[q][0], zd[q][1]), z0, z1, z2, z3);
;             *(uint2*)yp = pack4(vv[0] * z0, vv[1] * z1, vv[2] * z2, vv[3] * z3);
;             const float ma = bf2f((bf16)za[q]), mb0 = __uint_as_float(zb[q] << 16), mb1 = __uint_as_float(zb[q] & 0xffff0000u), mc = bf2f((bf16)zc[q]);
;             ym[0] = f2bf(vv[3] * ma);
;             *(unsigned*)(ym + 1) = pack2(vv[2] * mb0, vv[1] * mb1);
;             if (cp != 0) ym[3] = f2bf(vv[0] * mc);
.LBB0_646:
	s_or_b64 exec, exec, s[0:1]
	v_lshlrev_b32_e32 v36, 16, v84
	v_and_b32_e32 v37, 0xffff0000, v84
	v_lshlrev_b32_e32 v38, 16, v85
	v_and_b32_e32 v39, 0xffff0000, v85
	v_pk_mul_f32 v[36:37], v[32:33], v[36:37]
	v_pk_mul_f32 v[38:39], v[34:35], v[38:39]
	v_cvt_pk_bf16_f32 v36, v36, v37
	v_cvt_pk_bf16_f32 v37, v38, v39
	v_lshlrev_b32_e32 v38, 16, v108
	v_mul_f32_e32 v35, v35, v38
	global_store_dwordx2 v[46:47], v[36:37], off offset:32
	v_lshlrev_b32_e32 v36, 16, v107
	v_and_b32_e32 v37, 0xffff0000, v107
	v_cvt_pk_bf16_f32 v38, v35, s0
	v_mov_b32_e32 v35, v33
	v_pk_mul_f32 v[34:35], v[34:35], v[36:37]
	s_nop 0
	v_cvt_pk_bf16_f32 v33, v34, v35
	v_lshlrev_b32_e32 v34, 16, v106
	v_mul_f32_e32 v32, v32, v34
	v_cvt_pk_bf16_f32 v34, v32, s0
	v_perm_b32 v32, v33, v38, s14
	v_alignbit_b32 v33, v34, v33, 16
	global_store_dwordx2 v[44:45], v[32:33], off offset:218
	v_lshl_add_u64 v[32:33], s[8:9], 0, v[80:81]
	v_lshl_add_u64 v[34:35], v[32:33], 0, v[186:187]
	v_mov_b32_e32 v97, v187
	v_lshl_add_u64 v[36:37], v[34:35], 0, v[96:97]
	v_lshl_add_u64 v[34:35], s[8:9], 0, v[82:83]
	v_lshl_add_u64 v[34:35], v[34:35], 0, v[96:97]
	v_lshl_add_u64 v[34:35], v[128:129], 1, v[34:35]
	global_load_dwordx2 v[54:55], v[36:37], off
	global_load_ushort v91, v[34:35], off offset:250
	global_load_dword v90, v[34:35], off offset:252
	v_mov_b32_e32 v80, 0
	v_mov_b32_e32 v89, 0
	s_and_saveexec_b64 s[0:1], vcc
	s_cbranch_execz .LBB0_648
	global_load_ushort v89, v[34:35], off offset:256
.LBB0_648:
	s_or_b64 exec, exec, s[0:1]
	v_lshl_add_u64 v[32:33], v[32:33], 0, v[96:97]
	v_lshl_add_u64 v[32:33], v[32:33], 0, v[186:187]
	global_load_dwordx2 v[52:53], v[32:33], off offset:32
	global_load_ushort v88, v[34:35], off offset:218
	global_load_dword v87, v[34:35], off offset:220
	global_load_ushort v85, v[34:35], off offset:224
	v_lshl_add_u64 v[32:33], s[8:9], 0, v[76:77]
	v_lshl_add_u64 v[34:35], v[32:33], 0, v[186:187]
	v_lshl_add_u64 v[36:37], v[34:35], 0, v[96:97]
	v_lshl_add_u64 v[34:35], s[8:9], 0, v[78:79]
	v_lshl_add_u64 v[34:35], v[34:35], 0, v[96:97]
	v_lshl_add_u64 v[34:35], v[128:129], 1, v[34:35]
	global_load_dwordx2 v[46:47], v[36:37], off
	global_load_ushort v86, v[34:35], off offset:250
	global_load_dword v84, v[34:35], off offset:252
	s_and_saveexec_b64 s[0:1], vcc
	s_cbranch_execz .LBB0_650
	global_load_ushort v80, v[34:35], off offset:256
.LBB0_650:
	s_or_b64 exec, exec, s[0:1]
	v_mov_b32_e32 v97, v187
	v_lshl_add_u64 v[32:33], v[32:33], 0, v[96:97]
	v_lshl_add_u64 v[32:33], v[32:33], 0, v[186:187]
	global_load_dwordx2 v[44:45], v[32:33], off offset:32
	global_load_ushort v83, v[34:35], off offset:218
	global_load_dword v82, v[34:35], off offset:220
	global_load_ushort v79, v[34:35], off offset:224
	v_lshl_add_u64 v[34:35], s[8:9], 0, v[72:73]
	v_lshl_add_u64 v[32:33], v[34:35], 0, v[186:187]
	v_lshl_add_u64 v[36:37], v[32:33], 0, v[96:97]
	v_lshl_add_u64 v[32:33], s[8:9], 0, v[74:75]
	v_lshl_add_u64 v[32:33], v[32:33], 0, v[96:97]
	v_lshl_add_u64 v[32:33], v[128:129], 1, v[32:33]
	global_load_dwordx2 v[38:39], v[36:37], off
	global_load_ushort v81, v[32:33], off offset:250
	global_load_dword v78, v[32:33], off offset:252
	v_mov_b32_e32 v72, 0
	v_mov_b32_e32 v77, 0
	s_and_saveexec_b64 s[0:1], vcc
	s_cbranch_execz .LBB0_652
	global_load_ushort v77, v[32:33], off offset:256
.LBB0_652:
	s_or_b64 exec, exec, s[0:1]
	v_lshl_add_u64 v[34:35], v[34:35], 0, v[96:97]
	v_lshl_add_u64 v[34:35], v[34:35], 0, v[186:187]
	global_load_dwordx2 v[36:37], v[34:35], off offset:32
	global_load_ushort v76, v[32:33], off offset:218
	global_load_dword v75, v[32:33], off offset:220
	global_load_ushort v73, v[32:33], off offset:224
	v_lshl_add_u64 v[32:33], s[8:9], 0, v[66:67]
	v_lshl_add_u64 v[34:35], v[32:33], 0, v[186:187]
	v_lshl_add_u64 v[60:61], s[8:9], 0, v[70:71]
	v_lshl_add_u64 v[34:35], v[34:35], 0, v[96:97]
	v_lshl_add_u64 v[60:61], v[60:61], 0, v[96:97]
	v_lshl_add_u64 v[60:61], v[128:129], 1, v[60:61]
	global_load_dwordx2 v[34:35], v[34:35], off
	s_nop 0
	global_load_ushort v74, v[60:61], off offset:250
	global_load_dword v71, v[60:61], off offset:252
	s_and_saveexec_b64 s[0:1], vcc
	s_cbranch_execz .LBB0_654
	global_load_ushort v72, v[60:61], off offset:256
.LBB0_654:
	s_or_b64 exec, exec, s[0:1]
	v_mov_b32_e32 v97, v187
	v_lshl_add_u64 v[32:33], v[32:33], 0, v[96:97]
	v_lshl_add_u64 v[32:33], v[32:33], 0, v[186:187]
	global_load_dwordx2 v[32:33], v[32:33], off offset:32
	s_nop 0
	global_load_ushort v70, v[60:61], off offset:218
	global_load_dword v67, v[60:61], off offset:220
	global_load_ushort v66, v[60:61], off offset:224
	v_lshl_add_u64 v[62:63], s[10:11], 0, v[64:65]
	v_lshl_add_u64 v[60:61], v[62:63], 0, v[186:187]
	v_lshl_add_u64 v[64:65], v[60:61], 0, v[96:97]
	v_lshl_add_u64 v[60:61], s[10:11], 0, v[68:69]
	s_waitcnt vmcnt(0)
	v_lshlrev_b32_e32 v89, 16, v89
	v_lshlrev_b32_e32 v80, 16, v80
	v_lshlrev_b32_e32 v77, 16, v77
	v_lshlrev_b32_e32 v72, 16, v72
	v_lshlrev_b32_e32 v68, 16, v54
	v_and_b32_e32 v69, 0xffff0000, v54
	v_lshlrev_b32_e32 v54, 16, v55
	v_and_b32_e32 v55, 0xffff0000, v55
	v_pk_mul_f32 v[68:69], v[28:29], v[68:69]
	v_pk_mul_f32 v[54:55], v[30:31], v[54:55]
	v_cvt_pk_bf16_f32 v68, v68, v69
	v_cvt_pk_bf16_f32 v69, v54, v55
	global_store_dwordx2 v[64:65], v[68:69], off
	v_lshlrev_b32_e32 v64, 16, v91
	v_mul_f32_e32 v31, v31, v64
	v_lshlrev_b32_e32 v54, 16, v90
	v_and_b32_e32 v55, 0xffff0000, v90
	v_cvt_pk_bf16_f32 v64, v31, s0
	v_mov_b32_e32 v31, v29
	v_lshl_add_u64 v[60:61], v[60:61], 0, v[96:97]
	v_pk_mul_f32 v[30:31], v[30:31], v[54:55]
	v_lshl_add_u64 v[60:61], v[128:129], 1, v[60:61]
	v_cvt_pk_bf16_f32 v29, v30, v31
	v_perm_b32 v30, v29, v64, s14
	global_store_short_d16_hi v[60:61], v29, off offset:254
	global_store_dword v[60:61], v30, off offset:250
	s_and_saveexec_b64 s[0:1], vcc
	s_cbranch_execz .LBB0_656
	v_mul_f32_e32 v28, v28, v89
	v_cvt_pk_bf16_f32 v28, v28, s0
	global_store_short v[60:61], v28, off offset:256
